# stack12 with the deferred weight-conversion split at CONV_KT 16 instead of 20
# baseline (speedup 1.0000x reference)
.LBB8_256:
	s_cmp_lt_i32 s92, 3
	s_mul_i32 s59, s59, s68
	s_cselect_b64 s[6:7], -1, 0
	s_sub_i32 s8, s58, s59
	s_sub_i32 s9, s8, s68
	s_cmp_ge_u32 s8, s68
	s_cselect_b32 s8, s9, s8
	s_sub_i32 s9, s8, s68
	s_cmp_ge_u32 s8, s68
	s_cselect_b32 s8, s9, s8
	s_xor_b32 s38, s8, s56
	s_sub_i32 s39, s38, s56
	s_mul_i32 s8, s39, 0x80
	s_and_b32 s8, s8, 0xffffff00
	s_cmpk_lt_i32 s39, 0xc0
	v_readlane_b32 s10, v254, 2
	s_cselect_b32 s67, s8, 0x6000
	v_readlane_b32 s11, v254, 3
	s_add_u32 s68, s10, 0x200000
	s_addc_u32 s69, s11, 0
	s_add_u32 s54, s10, 0x800000
	s_addc_u32 s55, s11, 0
	s_add_u32 s36, s10, 0xc800000
	s_addc_u32 s37, s11, 0
	s_add_u32 s90, s10, 0x2a000000
	s_addc_u32 s91, s11, 0
	s_add_u32 s8, s10, 0x2b000000
	s_addc_u32 s9, s11, 0
	v_writelane_b32 v254, s8, 41
	s_nop 1
	v_writelane_b32 v254, s9, 42
	s_add_u32 s8, s10, 0x2c000000
	s_addc_u32 s9, s11, 0
	v_writelane_b32 v254, s8, 43
	s_nop 1
	v_writelane_b32 v254, s9, 44
	s_add_u32 s8, s10, 0x2e000000
	s_addc_u32 s9, s11, 0
	v_writelane_b32 v254, s8, 45
	s_add_u32 s88, s10, 0x36000000
	s_addc_u32 s89, s11, 0
	v_writelane_b32 v254, s9, 46
	s_and_b64 s[34:35], s[6:7], s[0:1]
	s_mov_b64 s[0:1], s[92:93]
	v_writelane_b32 v254, s0, 47
	s_andn2_b64 vcc, exec, s[34:35]
	s_nop 0
	v_writelane_b32 v254, s1, 48
	v_writelane_b32 v254, s2, 49
	v_writelane_b32 v254, s3, 50
	v_writelane_b32 v254, s68, 51
	s_nop 1
	v_writelane_b32 v254, s69, 52
	s_cbranch_vccnz .LBB8_357
	v_readlane_b32 s0, v254, 40
	s_waitcnt vmcnt(13) lgkmcnt(2)
	v_mbcnt_lo_u32_b32 v10, -1, 0
	v_mbcnt_hi_u32_b32 v10, -1, v10
	s_cmpk_gt_i32 s2, 0x99f
	s_waitcnt lgkmcnt(0)
	v_add_u32_e32 v0, s0, v10
	s_nop 0
	v_readfirstlane_b32 s1, v0
	s_cbranch_scc1 .LBB8_279
	v_lshlrev_b32_e32 v1, 4, v0
	v_add_u32_e32 v2, 0x2000, v1
	v_ashrrev_i32_e32 v3, 31, v2
	v_lshrrev_b32_e32 v3, 22, v3
	v_add_u32_e32 v3, v2, v3
	v_ashrrev_i32_e32 v8, 10, v3
	v_mul_i32_i24_e32 v3, 0x400, v8
	v_sub_u32_e32 v2, v2, v3
	v_lshrrev_b32_e32 v3, 4, v2
	v_bitop3_b32 v2, v3, v2, 32 bitop3:0x6c
	v_ashrrev_i32_e32 v3, 31, v2
	v_lshrrev_b32_e32 v3, 26, v3
	v_add_u32_e32 v3, v2, v3
	v_lshlrev_b32_e32 v4, 3, v8
	v_ashrrev_i32_e32 v9, 6, v3
	v_and_b32_e32 v4, -16, v4
	v_add_u32_e32 v4, v9, v4
	v_and_b32_e32 v5, 3, v9
	s_mov_b32 s0, 0x7ffe0
	v_lshrrev_b32_e32 v6, 2, v4
	v_lshlrev_b32_e32 v7, 1, v4
	v_and_b32_e32 v3, 0xc0, v3
	v_and_or_b32 v5, v4, s0, v5
	v_and_b32_e32 v6, 4, v6
	v_and_b32_e32 v7, 24, v7
	v_sub_u32_e32 v2, v2, v3
	v_mov_b32_e32 v3, 1
	v_or3_b32 v5, v5, v6, v7
	v_lshlrev_b32_e32 v6, 5, v8
	v_ashrrev_i16_sdwa v2, v3, sext(v2) dst_sel:DWORD dst_unused:UNUSED_PAD src0_sel:DWORD src1_sel:BYTE_0
	v_and_b32_e32 v6, 32, v6
	v_bfe_i32 v11, v2, 0, 16
	v_add_lshl_u32 v2, v6, v11, 1
	v_lshl_add_u32 v128, v5, 13, v2
	v_lshl_add_u32 v130, v4, 13, v2
	v_bfe_i32 v2, v0, 27, 1
	v_lshrrev_b32_e32 v2, 22, v2
	v_add_u32_e32 v2, v1, v2
	v_and_b32_e32 v2, 0xfffffc00, v2
	v_sub_u32_e32 v1, v1, v2
	v_lshrrev_b32_e32 v2, 4, v1
	v_ashrrev_i32_e32 v4, 31, v0
	v_bitop3_b32 v1, v2, v1, 32 bitop3:0x6c
	v_lshrrev_b32_e32 v4, 26, v4
	v_ashrrev_i32_e32 v2, 31, v1
	v_add_u32_e32 v0, v0, v4
	v_lshrrev_b32_e32 v2, 26, v2
	s_waitcnt vmcnt(12)
	v_ashrrev_i32_e32 v13, 6, v0
	v_add_u32_e32 v2, v1, v2
	v_lshlrev_b32_e32 v0, 3, v13
	v_ashrrev_i32_e32 v12, 6, v2
	v_and_b32_e32 v0, -16, v0
	v_add_u32_e32 v0, v12, v0
	v_and_b32_e32 v4, 3, v12
	s_ashr_i32 s58, s2, 31
	v_and_or_b32 v4, v0, s0, v4
	s_lshr_b32 s0, s58, 29
	s_add_i32 s0, s2, s0
	s_ashr_i32 s8, s1, 6
	s_ashr_i32 s6, s0, 3
	s_and_b32 s0, s0, -8
	s_ashr_i32 s10, s1, 8
	s_lshl_b32 s57, s8, 10
	s_sub_i32 s0, s2, s0
	s_cmp_lt_i32 s0, 0
	s_movk_i32 s59, 0x135
	s_cselect_b32 s7, s59, 0x134
	s_mul_i32 s0, s0, s7
	s_add_i32 s0, s0, s6
	s_mul_hi_i32 s6, s0, 0x3531dec1
	s_lshr_b32 s7, s6, 31
	s_ashr_i32 s6, s6, 7
	s_add_i32 s6, s6, s7
	s_lshl_b32 s7, s6, 3
	s_mulk_i32 s6, 0x268
	s_sub_i32 s6, s0, s6
	s_sext_i32_i16 s0, s6
	s_bfe_u32 s0, s0, 0x3001c
	s_add_i32 s9, s6, s0
	s_sext_i32_i16 s0, s9
	s_and_b32 s9, s9, 0xfff8
	s_sub_i32 s6, s6, s9
	s_sext_i32_i16 s6, s6
	v_lshrrev_b32_e32 v5, 2, v0
	v_lshlrev_b32_e32 v6, 1, v0
	v_and_b32_e32 v2, 0xc0, v2
	s_lshr_b32 s0, s0, 3
	s_add_i32 s68, s7, s6
	v_and_b32_e32 v5, 4, v5
	v_and_b32_e32 v6, 24, v6
	v_sub_u32_e32 v1, v1, v2
	s_ashr_i32 s69, s68, 31
	s_bfe_i64 s[12:13], s[0:1], 0x100000
	v_or3_b32 v4, v4, v5, v6
	v_lshlrev_b32_e32 v5, 5, v13
	v_ashrrev_i16_sdwa v1, v3, sext(v1) dst_sel:DWORD dst_unused:UNUSED_PAD src0_sel:DWORD src1_sel:BYTE_0
	s_lshl_b64 s[6:7], s[68:69], 21
	s_lshl_b64 s[12:13], s[12:13], 21
	v_and_b32_e32 v5, 32, v5
	v_bfe_i32 v14, v1, 0, 16
	s_add_u32 s28, s4, s12
	v_add_lshl_u32 v1, v5, v14, 1
	s_addc_u32 s29, s5, s13
	s_add_i32 s69, s57, 0
	v_lshl_add_u32 v132, v4, 13, v1
	s_add_i32 m0, s69, 0x10000
	v_lshl_add_u32 v134, v0, 13, v1
	global_load_lds_dwordx4 v132, s[28:29]
	s_add_i32 m0, s69, 0x12000
	s_add_u32 s12, s28, 0x100000
	global_load_lds_dwordx4 v128, s[28:29]
	s_addc_u32 s13, s29, 0
	s_add_i32 m0, s69, 0x14000
	v_mov_b32_e32 v133, 0
	global_load_lds_dwordx4 v132, s[12:13]
	s_add_i32 m0, s69, 0x16000
	s_add_u32 s70, s54, s6
	s_addc_u32 s71, s55, s7
	s_add_i32 s74, s69, 0x2000
	global_load_lds_dwordx4 v128, s[12:13]
	s_mov_b32 m0, s69
	s_add_u32 s6, s70, 0x100000
	global_load_lds_dwordx4 v134, s[70:71]
	s_mov_b32 m0, s74
	s_addc_u32 s7, s71, 0
	s_add_i32 s75, s69, 0x4000
	global_load_lds_dwordx4 v130, s[70:71]
	s_mov_b32 m0, s75
	s_add_i32 s76, s69, 0x6000
	global_load_lds_dwordx4 v134, s[6:7]
	s_mov_b32 m0, s76
	v_mov_b32_e32 v129, v133
	global_load_lds_dwordx4 v130, s[6:7]
	v_mov_b32_e32 v135, v133
	v_mov_b32_e32 v131, v133
	s_cmp_eq_u32 s10, 1
	s_mov_b32 s77, 0
	v_lshl_add_u64 v[6:7], s[28:29], 0, v[132:133]
	v_lshl_add_u64 v[4:5], s[28:29], 0, v[128:129]
	v_lshl_add_u64 v[0:1], s[70:71], 0, v[134:135]
	s_cselect_b64 s[6:7], -1, 0
	s_cmp_lg_u32 s10, 1
	v_lshl_add_u64 v[2:3], s[70:71], 0, v[130:131]
	s_cbranch_scc1 .LBB8_260
	s_barrier
